# v2 + wave 1 warms L2 with the next GEMM phase weight K-tiles 0/1 (LDS-DMA into unused LDS) while the XCD barrier spins (G2, Q, O phases)
# speedup vs baseline: 1.0048x; 1.0048x over previous
; __global__ void __launch_bounds__(NWAVES * 64, 2) fwd(Args args) {
;     ...
;             const bf16_t* W2 = ((l & 1) ? ((bf16_t*)(F.ws + WS_C2)) : ((bf16_t*)(F.ws + WS_AB2))) + (size_t)j * D * 2048;
;             pg8::Gemm g{((bf16_t*)(F.ws + WS_A2)), W2, MP, D, 2048}; pg8::StaticOrder S; S.init(MP, D, F.G, (int)F.vid);
.LBB0_973:
	s_or_b64 exec, exec, s[6:7]
	s_branch .LBB0_974
.Lpf_0:
	v_readlane_b32 vcc_lo, v254, 9
	s_nop 3
	s_cmp_eq_u32 vcc_lo, 1
	s_cbranch_scc0 .LBB0_974
	v_readlane_b32 s100, v254, 12
	v_readlane_b32 s101, v254, 13
	v_readlane_b32 vcc_lo, v254, 32
	v_readlane_b32 vcc_hi, v254, 0
	s_nop 3
	s_load_dwordx2 s[100:101], s[100:101], 0xd0
	v_mbcnt_lo_u32_b32 v0, -1, 0
	v_mbcnt_hi_u32_b32 v0, -1, v0
	v_lshrrev_b32_e32 v1, 4, v0
	v_and_b32_e32 v0, 15, v0
	v_lshlrev_b32_e32 v1, 12, v1
	v_lshl_or_b32 v0, v0, 4, v1
	s_lshr_b32 vcc_hi, vcc_hi, 3
	s_lshl_b32 vcc_hi, vcc_hi, 17
	s_lshr_b32 vcc_lo, vcc_lo, 1
	s_lshl_b32 vcc_lo, vcc_lo, 22
	s_add_u32 vcc_lo, vcc_lo, vcc_hi
	s_add_u32 vcc_lo, vcc_lo, 0x3e00000
	s_waitcnt lgkmcnt(0)
	s_add_u32 s100, s100, vcc_lo
	s_addc_u32 s101, s101, 0
	s_mov_b32 m0, 0x24000
	s_nop 0
	global_load_lds_dwordx4 v0, s[100:101]
	s_add_u32 s100, s100, 0x4000
	s_addc_u32 s101, s101, 0
	s_mov_b32 m0, 0x24400
	s_nop 0
	global_load_lds_dwordx4 v0, s[100:101]
	s_add_u32 s100, s100, 0x4000
	s_addc_u32 s101, s101, 0
	s_mov_b32 m0, 0x24800
	s_nop 0
	global_load_lds_dwordx4 v0, s[100:101]
	s_add_u32 s100, s100, 0x4000
	s_addc_u32 s101, s101, 0
	s_mov_b32 m0, 0x24c00
	s_nop 0
	global_load_lds_dwordx4 v0, s[100:101]
	s_add_u32 s100, s100, 0x4000
	s_addc_u32 s101, s101, 0
	s_mov_b32 m0, 0x25000
	s_nop 0
	global_load_lds_dwordx4 v0, s[100:101]
	s_add_u32 s100, s100, 0x4000
	s_addc_u32 s101, s101, 0
	s_mov_b32 m0, 0x25400
	s_nop 0
	global_load_lds_dwordx4 v0, s[100:101]
	s_add_u32 s100, s100, 0x4000
	s_addc_u32 s101, s101, 0
	s_mov_b32 m0, 0x25800
	s_nop 0
	global_load_lds_dwordx4 v0, s[100:101]
	s_add_u32 s100, s100, 0x4000
	s_addc_u32 s101, s101, 0
	s_mov_b32 m0, 0x25c00
	s_nop 0
	global_load_lds_dwordx4 v0, s[100:101]
	s_branch .LBB0_974

; __global__ void __launch_bounds__(NWAVES * 64, 2) fwd(Args args) {
;     ...
;             const bf16_t* W2 = ((l & 1) ? ((bf16_t*)(F.ws + WS_C2)) : ((bf16_t*)(F.ws + WS_AB2))) + (size_t)j * D * 2048;
;             pg8::Gemm g{((bf16_t*)(F.ws + WS_A2)), W2, MP, D, 2048}; pg8::StaticOrder S; S.init(MP, D, F.G, (int)F.vid);
.LBB0_1692:
	s_or_b64 exec, exec, s[2:3]
	s_branch .LBB0_1693
.Lpf_1:
	v_readlane_b32 vcc_lo, v254, 9
	s_nop 3
	s_cmp_eq_u32 vcc_lo, 1
	s_cbranch_scc0 .LBB0_1693
	v_readlane_b32 s100, v254, 12
	v_readlane_b32 s101, v254, 13
	v_readlane_b32 vcc_lo, v254, 32
	v_readlane_b32 vcc_hi, v254, 0
	s_nop 3
	s_load_dwordx2 s[100:101], s[100:101], 0xd0
	v_mbcnt_lo_u32_b32 v0, -1, 0
	v_mbcnt_hi_u32_b32 v0, -1, v0
	v_lshrrev_b32_e32 v1, 4, v0
	v_and_b32_e32 v0, 15, v0
	v_lshlrev_b32_e32 v1, 12, v1
	v_lshl_or_b32 v0, v0, 4, v1
	s_lshr_b32 vcc_hi, vcc_hi, 3
	s_lshl_b32 vcc_hi, vcc_hi, 17
	s_lshr_b32 vcc_lo, vcc_lo, 1
	s_lshl_b32 vcc_lo, vcc_lo, 22
	s_add_u32 vcc_lo, vcc_lo, vcc_hi
	s_add_u32 vcc_lo, vcc_lo, 0x3600000
	s_waitcnt lgkmcnt(0)
	s_add_u32 s100, s100, vcc_lo
	s_addc_u32 s101, s101, 0
	s_mov_b32 m0, 0x24000
	s_nop 0
	global_load_lds_dwordx4 v0, s[100:101]
	s_add_u32 s100, s100, 0x4000
	s_addc_u32 s101, s101, 0
	s_mov_b32 m0, 0x24400
	s_nop 0
	global_load_lds_dwordx4 v0, s[100:101]
	s_add_u32 s100, s100, 0x4000
	s_addc_u32 s101, s101, 0
	s_mov_b32 m0, 0x24800
	s_nop 0
	global_load_lds_dwordx4 v0, s[100:101]
	s_add_u32 s100, s100, 0x4000
	s_addc_u32 s101, s101, 0
	s_mov_b32 m0, 0x24c00
	s_nop 0
	global_load_lds_dwordx4 v0, s[100:101]
	s_add_u32 s100, s100, 0x4000
	s_addc_u32 s101, s101, 0
	s_mov_b32 m0, 0x25000
	s_nop 0
	global_load_lds_dwordx4 v0, s[100:101]
	s_add_u32 s100, s100, 0x4000
	s_addc_u32 s101, s101, 0
	s_mov_b32 m0, 0x25400
	s_nop 0
	global_load_lds_dwordx4 v0, s[100:101]
	s_add_u32 s100, s100, 0x4000
	s_addc_u32 s101, s101, 0
	s_mov_b32 m0, 0x25800
	s_nop 0
	global_load_lds_dwordx4 v0, s[100:101]
	s_add_u32 s100, s100, 0x4000
	s_addc_u32 s101, s101, 0
	s_mov_b32 m0, 0x25c00
	s_nop 0
	global_load_lds_dwordx4 v0, s[100:101]
	s_branch .LBB0_1693

; #define LAS __attribute__((address_space(3)))
; #define REP(bit) for (int rep_ = 0; rep_ < 1 + ((REP_MASK >> (bit)) & 1); ++rep_)
; __global__ void __launch_bounds__(NWAVES * 64, 2) fwd(Args args) {
;     ...
;             pg8::Gemm g{((bf16_t*)(F.ws + WS_XB)), ((bf16_t*)(F.ws + WS_WQ)) + (size_t)l * D * D, MP, D, D}; pg8::StaticOrder S; S.init(MP, D, F.G, (int)F.vid);
;             Unit u0{0, 0}; S.next(0, u0);
;             EpiQ E{((float*)(F.ws + WS_RSQ)), ((bf16_t*)(F.ws + WS_Q)), (LAS const float*)(F.lds + RSTD_OFF), u0.pm};
;             REP(8) pg8::gemm_phase<EpiQ, pg8::StaticOrder, true, true>(F.lds, g, S, E, F.wave);
.LBB0_1832:
	s_or_b64 exec, exec, s[4:5]
	s_branch .LBB0_1833
.Lpf_2:
	v_readlane_b32 vcc_lo, v254, 9
	s_nop 3
	s_cmp_eq_u32 vcc_lo, 1
	s_cbranch_scc0 .LBB0_1833
	v_readlane_b32 s100, v254, 12
	v_readlane_b32 s101, v254, 13
	v_readlane_b32 vcc_lo, v254, 32
	v_readlane_b32 vcc_hi, v254, 0
	s_nop 3
	s_load_dwordx2 s[100:101], s[100:101], 0xd0
	v_mbcnt_lo_u32_b32 v0, -1, 0
	v_mbcnt_hi_u32_b32 v0, -1, v0
	v_lshrrev_b32_e32 v1, 4, v0
	v_and_b32_e32 v0, 15, v0
	v_lshlrev_b32_e32 v1, 11, v1
	v_lshl_or_b32 v0, v0, 4, v1
	s_lshr_b32 vcc_hi, vcc_hi, 3
	s_lshl_b32 vcc_hi, vcc_hi, 16
	s_lshl_b32 vcc_lo, vcc_lo, 21
	s_add_u32 vcc_lo, vcc_lo, vcc_hi
	s_add_u32 vcc_lo, vcc_lo, 0x4600000
	s_waitcnt lgkmcnt(0)
	s_add_u32 s100, s100, vcc_lo
	s_addc_u32 s101, s101, 0
	s_mov_b32 m0, 0x24000
	s_nop 0
	global_load_lds_dwordx4 v0, s[100:101]
	s_add_u32 s100, s100, 0x2000
	s_addc_u32 s101, s101, 0
	s_mov_b32 m0, 0x24400
	s_nop 0
	global_load_lds_dwordx4 v0, s[100:101]
	s_add_u32 s100, s100, 0x2000
	s_addc_u32 s101, s101, 0
	s_mov_b32 m0, 0x24800
	s_nop 0
	global_load_lds_dwordx4 v0, s[100:101]
	s_add_u32 s100, s100, 0x2000
	s_addc_u32 s101, s101, 0
	s_mov_b32 m0, 0x24c00
	s_nop 0
	global_load_lds_dwordx4 v0, s[100:101]
	s_add_u32 s100, s100, 0x2000
	s_addc_u32 s101, s101, 0
	s_mov_b32 m0, 0x25000
	s_nop 0
	global_load_lds_dwordx4 v0, s[100:101]
	s_add_u32 s100, s100, 0x2000
	s_addc_u32 s101, s101, 0
	s_mov_b32 m0, 0x25400
	s_nop 0
	global_load_lds_dwordx4 v0, s[100:101]
	s_add_u32 s100, s100, 0x2000
	s_addc_u32 s101, s101, 0
	s_mov_b32 m0, 0x25800
	s_nop 0
	global_load_lds_dwordx4 v0, s[100:101]
	s_add_u32 s100, s100, 0x2000
	s_addc_u32 s101, s101, 0
	s_mov_b32 m0, 0x25c00
	s_nop 0
	global_load_lds_dwordx4 v0, s[100:101]
	s_branch .LBB0_1833

; __global__ void __launch_bounds__(NWAVES * 64, 2) fwd(Args args) {
;     ...
;             pg8::Gemm g{((bf16_t*)(F.ws + WS_O)), ((bf16_t*)(F.ws + WS_WO)) + (size_t)l * D * D, MP, D, D}; pg8::StaticOrder S; S.init(MP, D, F.G, (int)F.vid);
;             EpiRes E{((bf16_t*)(F.ws + WS_XB)), ((float*)(F.ws + WS_RSQ))};
;             pg8::gemm_phase<EpiRes, pg8::StaticOrder, true, true>(F.lds, g, S, E, F.wave);
.Lpf_3:
	v_readlane_b32 vcc_lo, v254, 9
	s_nop 3
	s_cmp_eq_u32 vcc_lo, 1
	s_cbranch_scc0 .LBB0_2213
	v_readlane_b32 s100, v254, 12
	v_readlane_b32 s101, v254, 13
	v_readlane_b32 vcc_lo, v254, 32
	v_readlane_b32 vcc_hi, v254, 0
	s_nop 3
	s_load_dwordx2 s[100:101], s[100:101], 0xd0
	v_mbcnt_lo_u32_b32 v0, -1, 0
	v_mbcnt_hi_u32_b32 v0, -1, v0
	v_lshrrev_b32_e32 v1, 4, v0
	v_and_b32_e32 v0, 15, v0
	v_lshlrev_b32_e32 v1, 11, v1
	v_lshl_or_b32 v0, v0, 4, v1
	s_lshr_b32 vcc_hi, vcc_hi, 3
	s_lshl_b32 vcc_hi, vcc_hi, 16
	s_lshl_b32 vcc_lo, vcc_lo, 21
	s_add_u32 vcc_lo, vcc_lo, vcc_hi
	s_add_u32 vcc_lo, vcc_lo, 0x5e00000
	s_waitcnt lgkmcnt(0)
	s_add_u32 s100, s100, vcc_lo
	s_addc_u32 s101, s101, 0
	s_mov_b32 m0, 0x24000
	s_nop 0
	global_load_lds_dwordx4 v0, s[100:101]
	s_add_u32 s100, s100, 0x2000
	s_addc_u32 s101, s101, 0
	s_mov_b32 m0, 0x24400
	s_nop 0
	global_load_lds_dwordx4 v0, s[100:101]
	s_add_u32 s100, s100, 0x2000
	s_addc_u32 s101, s101, 0
	s_mov_b32 m0, 0x24800
	s_nop 0
	global_load_lds_dwordx4 v0, s[100:101]
	s_add_u32 s100, s100, 0x2000
	s_addc_u32 s101, s101, 0
	s_mov_b32 m0, 0x24c00
	s_nop 0
	global_load_lds_dwordx4 v0, s[100:101]
	s_add_u32 s100, s100, 0x2000
	s_addc_u32 s101, s101, 0
	s_mov_b32 m0, 0x25000
	s_nop 0
	global_load_lds_dwordx4 v0, s[100:101]
	s_add_u32 s100, s100, 0x2000
	s_addc_u32 s101, s101, 0
	s_mov_b32 m0, 0x25400
	s_nop 0
	global_load_lds_dwordx4 v0, s[100:101]
	s_add_u32 s100, s100, 0x2000
	s_addc_u32 s101, s101, 0
	s_mov_b32 m0, 0x25800
	s_nop 0
	global_load_lds_dwordx4 v0, s[100:101]
	s_add_u32 s100, s100, 0x2000
	s_addc_u32 s101, s101, 0
	s_mov_b32 m0, 0x25c00
	s_nop 0
	global_load_lds_dwordx4 v0, s[100:101]
	s_branch .LBB0_2213
